# attention PV: counted lgkmcnt per V fragment + first V fragment read hoisted ahead of QK MFMAs
# baseline (speedup 1.0000x reference)
.LBB0_185:
	s_and_b64 vcc, exec, s[26:27]
	s_cbranch_vccz .LBB0_199
	s_lshl_b32 s22, s33, 14
	s_add_i32 s22, s22, 0
	s_nop 1
	ds_read_b128 v[126:129], v249 offset:49152
	s_waitcnt lgkmcnt(1)
	v_mfma_f32_32x32x16_bf16 v[82:97], v[98:101], v[146:149], v[66:81]
	ds_read_b128 v[122:125], v102 offset:8192
	v_mfma_f32_32x32x16_bf16 v[98:113], v[114:117], v[146:149], v[66:81]
	v_add_u32_e32 v139, s22, v241
	ds_read_b128 v[114:117], v139
	v_mfma_f32_32x32x16_bf16 v[82:97], v[118:121], v[150:153], v[82:97]
	ds_read_b128 v[118:121], v139 offset:8192
	s_waitcnt lgkmcnt(0)
	v_mfma_f32_32x32x16_bf16 v[98:113], v[122:125], v[150:153], v[98:113]
	v_add_u32_e32 v139, s22, v243
	ds_read_b128 v[122:125], v139
	v_mfma_f32_32x32x16_bf16 v[82:97], v[114:117], v[154:157], v[82:97]
	ds_read_b128 v[114:117], v139 offset:8192
	v_mfma_f32_32x32x16_bf16 v[98:113], v[118:121], v[154:157], v[98:113]
	s_waitcnt lgkmcnt(0)
	v_mfma_f32_32x32x16_bf16 v[82:97], v[122:125], v[158:161], v[82:97]
	v_mfma_f32_32x32x16_bf16 v[98:113], v[114:117], v[158:161], v[98:113]
	s_nop 0
	ds_read_b128 v[122:125], v249 offset:53248
	ds_read_b128 v[118:121], v249 offset:57344
	ds_read_b128 v[114:117], v249 offset:61440
	s_add_i32 s22, s21, 64
	s_cmp_le_u32 s22, s20
	s_cbranch_scc1 .LBB0_188
	v_add_u32_e32 v130, s21, v248
	v_add_u32_e32 v130, 0x11f, v130
	v_and_b32_e32 v130, 0x3ffffffc, v130
	v_lshl_add_u32 v166, v130, 2, v0
	ds_read_b128 v[130:133], v166
	ds_read_b128 v[134:137], v166 offset:16
	ds_read_b128 v[138:141], v166 offset:64
	ds_read_b128 v[142:145], v166 offset:80
	s_waitcnt lgkmcnt(0)
	v_pk_add_f32 v[84:85], v[84:85], v[132:133]
	v_pk_add_f32 v[86:87], v[86:87], v[134:135]
	v_pk_add_f32 v[90:91], v[90:91], v[138:139]
	v_pk_add_f32 v[94:95], v[94:95], v[142:143]
	v_pk_add_f32 v[96:97], v[96:97], v[144:145]
	v_pk_add_f32 v[92:93], v[92:93], v[140:141]
	v_pk_add_f32 v[88:89], v[88:89], v[136:137]
	v_pk_add_f32 v[82:83], v[82:83], v[130:131]
	ds_read_b128 v[130:133], v166 offset:128
	ds_read_b128 v[134:137], v166 offset:144
	ds_read_b128 v[138:141], v166 offset:192
	ds_read_b128 v[142:145], v166 offset:208
	s_waitcnt lgkmcnt(0)
	v_pk_add_f32 v[100:101], v[100:101], v[132:133]
	v_pk_add_f32 v[102:103], v[102:103], v[134:135]
	v_pk_add_f32 v[106:107], v[106:107], v[138:139]
	v_pk_add_f32 v[110:111], v[110:111], v[142:143]
	v_pk_add_f32 v[112:113], v[112:113], v[144:145]
	v_pk_add_f32 v[108:109], v[108:109], v[140:141]
	v_pk_add_f32 v[104:105], v[104:105], v[136:137]
	v_pk_add_f32 v[98:99], v[98:99], v[130:131]
.LBB0_188:
	s_waitcnt lgkmcnt(3)
	v_mfma_f32_32x32x16_bf16 v[34:49], v[126:129], v[162:165], v[34:49]
	ds_read_b128 v[126:129], v212 offset:49152
	s_nop 0
	v_exp_f32_e32 v130, v82
	v_exp_f32_e32 v131, v83
	v_add_f32_e32 v132, v1, v130
	v_add_f32_e32 v133, v1, v131
	v_cvt_pk_bf16_f32 v166, v130, v131
	s_waitcnt lgkmcnt(3)
	v_mfma_f32_32x32x16_bf16 v[50:65], v[122:125], v[162:165], v[50:65]
	ds_read_b128 v[122:125], v212 offset:53248
	v_exp_f32_e32 v134, v84
	v_exp_f32_e32 v135, v85
	s_add_i32 s22, s23, 2
	s_cmp_lt_u32 s22, s17
	v_add_f32_e32 v130, v132, v134
	v_add_f32_e32 v131, v133, v135
	v_cvt_pk_bf16_f32 v167, v134, v135
	s_cselect_b64 s[26:27], -1, 0
	s_cmp_ge_u32 s22, s17
	s_cbranch_scc1 .LBB0_190
	s_lshl_b32 s40, s48, 14
	s_add_i32 m0, s11, s40
	s_add_u32 s100, s8, s80
	s_addc_u32 s101, s9, s81
	global_load_lds_dwordx4 v214, s[100:101]
.LBB0_190:
	s_waitcnt lgkmcnt(3)
	v_mfma_f32_32x32x16_bf16 v[18:33], v[118:121], v[162:165], v[18:33]
	ds_read_b128 v[118:121], v212 offset:57344
	v_exp_f32_e32 v132, v86
	v_exp_f32_e32 v133, v87
	v_add_f32_e32 v130, v130, v132
	v_add_f32_e32 v131, v131, v133
	v_cvt_pk_bf16_f32 v168, v132, v133
	s_waitcnt lgkmcnt(3)
	v_mfma_f32_32x32x16_bf16 v[2:17], v[114:117], v[162:165], v[2:17]
	ds_read_b128 v[114:117], v212 offset:61440
	v_exp_f32_e32 v132, v88
	v_exp_f32_e32 v133, v89
	v_add_f32_e32 v134, v130, v132
	v_add_f32_e32 v131, v131, v133
	v_cvt_pk_bf16_f32 v169, v132, v133
	s_waitcnt lgkmcnt(3)
	v_mfma_f32_32x32x16_bf16 v[34:49], v[126:129], v[170:173], v[34:49]
	v_add_u32_e32 v130, s54, v246
	ds_read_b128 v[126:129], v130 offset:49152
	v_exp_f32_e32 v132, v90
	v_exp_f32_e32 v133, v91
	v_add_f32_e32 v134, v134, v132
	v_add_f32_e32 v135, v131, v133
	v_cvt_pk_bf16_f32 v174, v132, v133
	s_waitcnt lgkmcnt(3)
	v_mfma_f32_32x32x16_bf16 v[50:65], v[122:125], v[170:173], v[50:65]
	ds_read_b128 v[122:125], v130 offset:53248
	v_exp_f32_e32 v133, v92
	v_exp_f32_e32 v136, v93
	v_add_f32_e32 v131, v134, v133
	v_add_f32_e32 v132, v135, v136
	s_andn2_b64 vcc, exec, s[26:27]
	v_cvt_pk_bf16_f32 v175, v133, v136
	s_cbranch_vccnz .LBB0_192
	s_lshl_b32 s26, s48, 14
	s_add_i32 s26, s11, s26
	s_add_i32 m0, s26, 0x2000
	s_add_u32 s100, s8, s62
	s_addc_u32 s101, s9, s63
	global_load_lds_dwordx4 v214, s[100:101]
.LBB0_192:
	s_waitcnt lgkmcnt(3)
	v_mfma_f32_32x32x16_bf16 v[18:33], v[118:121], v[170:173], v[18:33]
	ds_read_b128 v[118:121], v130 offset:57344
	v_exp_f32_e32 v133, v94
	v_exp_f32_e32 v134, v95
	v_add_f32_e32 v131, v131, v133
	v_add_f32_e32 v132, v132, v134
	v_cvt_pk_bf16_f32 v176, v133, v134
	s_waitcnt lgkmcnt(3)
	v_mfma_f32_32x32x16_bf16 v[2:17], v[114:117], v[170:173], v[2:17]
	ds_read_b128 v[114:117], v130 offset:61440
	v_exp_f32_e32 v130, v96
	v_exp_f32_e32 v133, v97
	v_add_f32_e32 v131, v131, v130
	v_add_f32_e32 v132, v132, v133
	v_cvt_pk_bf16_f32 v177, v130, v133
	s_waitcnt lgkmcnt(3)
	v_mfma_f32_32x32x16_bf16 v[34:49], v[126:129], v[178:181], v[34:49]
	v_add_u32_e32 v130, s54, v247
	ds_read_b128 v[126:129], v130 offset:49152
	v_exp_f32_e32 v133, v98
	v_exp_f32_e32 v134, v99
	v_add_f32_e32 v131, v131, v133
	v_add_f32_e32 v132, v132, v134
	v_cvt_pk_bf16_f32 v182, v133, v134
	s_waitcnt lgkmcnt(3)
	v_mfma_f32_32x32x16_bf16 v[50:65], v[122:125], v[178:181], v[50:65]
	v_exp_f32_e32 v133, v100
	v_exp_f32_e32 v134, v101
	ds_read_b128 v[122:125], v130 offset:53248
	v_add_f32_e32 v131, v131, v133
	v_add_f32_e32 v132, v132, v134
	v_cvt_pk_bf16_f32 v183, v133, v134
	v_cndmask_b32_e64 v133, 0, 1, s[88:89]
	v_cmp_ne_u32_e64 s[40:41], 1, v133
	s_andn2_b64 vcc, exec, s[88:89]
	s_cbranch_vccnz .LBB0_194
	s_lshl_b32 s26, s31, 14
	s_add_i32 s26, s11, s26
	s_add_i32 m0, s26, 0xc000
	s_add_u32 s100, s8, s96
	s_addc_u32 s101, s9, s97
	global_load_lds_dwordx4 v216, s[100:101]
.LBB0_194:
	s_waitcnt lgkmcnt(3)
	v_mfma_f32_32x32x16_bf16 v[18:33], v[118:121], v[178:181], v[18:33]
	ds_read_b128 v[118:121], v130 offset:57344
	v_exp_f32_e32 v133, v102
	v_exp_f32_e32 v134, v103
	v_add_f32_e32 v131, v131, v133
	v_add_f32_e32 v132, v132, v134
	v_cvt_pk_bf16_f32 v184, v133, v134
	s_waitcnt lgkmcnt(3)
	v_mfma_f32_32x32x16_bf16 v[2:17], v[114:117], v[178:181], v[2:17]
	ds_read_b128 v[114:117], v130 offset:61440
	v_exp_f32_e32 v130, v104
	v_exp_f32_e32 v133, v105
	v_add_f32_e32 v131, v131, v130
	v_add_f32_e32 v132, v132, v133
	v_cvt_pk_bf16_f32 v185, v130, v133
	s_waitcnt lgkmcnt(3)
	v_mfma_f32_32x32x16_bf16 v[34:49], v[126:129], v[186:189], v[34:49]
	v_exp_f32_e32 v126, v106
	v_exp_f32_e32 v127, v107
	v_add_f32_e32 v128, v131, v126
	v_add_f32_e32 v129, v132, v127
	v_cvt_pk_bf16_f32 v190, v126, v127
	s_waitcnt lgkmcnt(2)
	v_mfma_f32_32x32x16_bf16 v[50:65], v[122:125], v[186:189], v[50:65]
	v_exp_f32_e32 v124, v108
	v_exp_f32_e32 v125, v109
	v_add_f32_e32 v122, v128, v124
	v_add_f32_e32 v123, v129, v125
	s_and_b64 vcc, exec, s[40:41]
	v_cvt_pk_bf16_f32 v191, v124, v125
	s_cbranch_vccnz .LBB0_196
	s_lshl_b32 s26, s31, 14
	s_add_i32 s26, s11, s26
	s_add_i32 m0, s26, 0xe000
	s_add_u32 s100, s8, s58
	s_addc_u32 s101, s9, s59
	global_load_lds_dwordx4 v216, s[100:101]
.LBB0_196:
	s_waitcnt lgkmcnt(1)
	v_mfma_f32_32x32x16_bf16 v[18:33], v[118:121], v[186:189], v[18:33]
	v_exp_f32_e32 v118, v110
	v_exp_f32_e32 v119, v111
	v_add_f32_e32 v120, v122, v118
	v_add_f32_e32 v121, v123, v119
	v_cvt_pk_bf16_f32 v192, v118, v119
	s_waitcnt lgkmcnt(0)
	v_mfma_f32_32x32x16_bf16 v[2:17], v[114:117], v[186:189], v[2:17]
	v_exp_f32_e32 v114, v112
	v_exp_f32_e32 v115, v113
	v_add_f32_e32 v116, v120, v114
	v_add_f32_e32 v117, v121, v115
	v_cvt_pk_bf16_f32 v193, v114, v115
	v_add_f32_e32 v212, v116, v117
	v_cmp_nge_f32_e32 vcc, s7, v212
	s_cbranch_vccz .LBB0_198
	v_max_f32_e32 v66, v99, v99
	v_max_f32_e32 v67, v83, v83
	v_max_f32_e32 v66, v67, v66
	v_max3_f32 v66, v82, v98, v66
	v_max3_f32 v67, v100, v85, v101
	v_max3_f32 v66, v66, v84, v67
	v_max3_f32 v67, v102, v87, v103
	v_max3_f32 v66, v66, v86, v67
	v_max3_f32 v67, v104, v89, v105
	v_max3_f32 v66, v66, v88, v67
	v_max3_f32 v67, v106, v91, v107
	v_max3_f32 v66, v66, v90, v67
	v_max3_f32 v67, v108, v93, v109
	v_max3_f32 v66, v66, v92, v67
	v_max3_f32 v67, v110, v95, v111
	v_max3_f32 v66, v66, v94, v67
	v_max3_f32 v67, v112, v97, v113
	v_max3_f32 v66, v66, v96, v67
	v_mov_b32_e32 v67, v66
	s_nop 1
	v_permlane32_swap_b32_e32 v66, v67
	v_max_f32_e32 v67, v67, v67
	v_max_f32_e32 v66, v66, v66
	v_max_f32_e32 v66, v66, v67
	v_cmp_lt_f32_e32 vcc, s57, v66
	s_nop 1
	v_cndmask_b32_e32 v68, 0, v66, vcc
	v_sub_f32_e32 v66, v82, v68
	v_exp_f32_e32 v116, v66
	v_sub_f32_e32 v66, v98, v68
	v_exp_f32_e32 v117, v66
	v_sub_f32_e32 v66, v83, v68
	v_exp_f32_e32 v118, v66
	v_sub_f32_e32 v66, v99, v68
	v_exp_f32_e32 v119, v66
	v_sub_f32_e32 v66, v84, v68
	v_exp_f32_e32 v98, v66
	v_sub_f32_e32 v66, v100, v68
	v_exp_f32_e32 v82, v66
	v_add_f32_e32 v66, v117, v116
	v_add_f32_e32 v99, 0, v66
	v_add_f32_e32 v83, v119, v118
	v_pk_add_f32 v[66:67], v[82:83], v[98:99]
	v_cvt_pk_bf16_f32 v166, v116, v118
	v_pk_add_f32 v[114:115], v[66:67], v[66:67] op_sel_hi:[0,1]
	v_sub_f32_e32 v66, v85, v68
	v_exp_f32_e32 v83, v66
	v_sub_f32_e32 v66, v101, v68
	v_exp_f32_e32 v99, v66
	v_sub_f32_e32 v66, v86, v68
	v_exp_f32_e32 v114, v66
	v_sub_f32_e32 v66, v102, v68
	v_exp_f32_e32 v84, v66
	v_add_f32_e32 v85, v99, v83
	v_cvt_pk_bf16_f32 v167, v98, v83
	v_cvt_pk_bf16_f32 v182, v117, v119
	v_pk_add_f32 v[66:67], v[84:85], v[114:115]
	v_cvt_pk_bf16_f32 v183, v82, v99
	v_pk_add_f32 v[100:101], v[66:67], v[66:67] op_sel_hi:[0,1]
	v_sub_f32_e32 v66, v87, v68
	v_exp_f32_e32 v85, v66
	v_sub_f32_e32 v66, v103, v68
	v_exp_f32_e32 v115, v66
	v_sub_f32_e32 v66, v88, v68
	v_exp_f32_e32 v100, v66
	v_sub_f32_e32 v66, v104, v68
	v_exp_f32_e32 v86, v66
	v_add_f32_e32 v87, v115, v85
	v_cvt_pk_bf16_f32 v168, v114, v85
	v_cvt_pk_bf16_f32 v184, v84, v115
	v_pk_add_f32 v[66:67], v[86:87], v[100:101]
	s_nop 0
	v_pk_add_f32 v[102:103], v[66:67], v[66:67] op_sel_hi:[0,1]
	v_sub_f32_e32 v66, v89, v68
	v_exp_f32_e32 v87, v66
	v_sub_f32_e32 v66, v105, v68
	v_exp_f32_e32 v101, v66
	v_sub_f32_e32 v66, v90, v68
	v_exp_f32_e32 v102, v66
	v_sub_f32_e32 v66, v106, v68
	v_exp_f32_e32 v88, v66
	v_add_f32_e32 v89, v101, v87
	v_cvt_pk_bf16_f32 v169, v100, v87
	v_cvt_pk_bf16_f32 v185, v86, v101
	v_pk_add_f32 v[66:67], v[88:89], v[102:103]
	s_nop 0
	v_pk_add_f32 v[104:105], v[66:67], v[66:67] op_sel_hi:[0,1]
	v_sub_f32_e32 v66, v91, v68
	v_exp_f32_e32 v89, v66
	v_sub_f32_e32 v66, v107, v68
	v_exp_f32_e32 v103, v66
	v_sub_f32_e32 v66, v92, v68
	v_exp_f32_e32 v104, v66
	v_sub_f32_e32 v66, v108, v68
	v_exp_f32_e32 v90, v66
	v_sub_f32_e32 v66, v97, v68
	v_add_f32_e32 v91, v103, v89
	v_exp_f32_e32 v97, v66
	v_pk_add_f32 v[66:67], v[90:91], v[104:105]
	v_cvt_pk_bf16_f32 v174, v102, v89
	v_pk_add_f32 v[106:107], v[66:67], v[66:67] op_sel_hi:[0,1]
	v_sub_f32_e32 v66, v93, v68
	v_exp_f32_e32 v91, v66
	v_sub_f32_e32 v66, v109, v68
	v_exp_f32_e32 v105, v66
	v_sub_f32_e32 v66, v94, v68
	v_exp_f32_e32 v106, v66
	v_sub_f32_e32 v66, v110, v68
	v_exp_f32_e32 v92, v66
	v_sub_f32_e32 v66, v113, v68
	v_add_f32_e32 v93, v105, v91
	v_exp_f32_e32 v110, v66
	v_pk_add_f32 v[66:67], v[92:93], v[106:107]
	v_cvt_pk_bf16_f32 v175, v104, v91
	v_pk_add_f32 v[108:109], v[66:67], v[66:67] op_sel_hi:[0,1]
	v_sub_f32_e32 v66, v95, v68
	v_exp_f32_e32 v93, v66
	v_sub_f32_e32 v66, v111, v68
	v_exp_f32_e32 v107, v66
	v_sub_f32_e32 v66, v96, v68
	v_exp_f32_e32 v108, v66
	v_sub_f32_e32 v66, v112, v68
	v_exp_f32_e32 v94, v66
	v_add_f32_e32 v95, v107, v93
	v_exp_f32_e64 v96, -v68
	v_add_f32_e32 v212, v110, v97
	v_pk_add_f32 v[66:67], v[94:95], v[108:109]
	v_cvt_pk_bf16_f32 v176, v106, v93
	v_pk_add_f32 v[66:67], v[66:67], v[66:67] op_sel:[0,1] op_sel_hi:[1,0]
	v_pk_mul_f32 v[48:49], v[48:49], v[96:97] op_sel_hi:[1,0]
	v_mov_b32_e32 v67, v68
	v_pk_add_f32 v[212:213], v[212:213], v[66:67]
	v_pk_mul_f32 v[46:47], v[46:47], v[96:97] op_sel_hi:[1,0]
	v_xor_b32_e32 v66, 0x80000000, v213
	v_mov_b32_e32 v67, v66
	v_mov_b32_e32 v68, v66
	v_mov_b32_e32 v69, v66
	v_mov_b32_e32 v70, v66
	v_mov_b32_e32 v71, v66
	v_mov_b32_e32 v72, v66
	v_mov_b32_e32 v73, v66
	v_mov_b32_e32 v74, v66
	v_mov_b32_e32 v75, v66
	v_mov_b32_e32 v76, v66
	v_mov_b32_e32 v77, v66
	v_mov_b32_e32 v78, v66
	v_mov_b32_e32 v79, v66
	v_mov_b32_e32 v80, v66
	v_mov_b32_e32 v81, v66
	v_pk_mul_f32 v[44:45], v[44:45], v[96:97] op_sel_hi:[1,0]
	v_pk_mul_f32 v[42:43], v[42:43], v[96:97] op_sel_hi:[1,0]
	v_pk_mul_f32 v[40:41], v[40:41], v[96:97] op_sel_hi:[1,0]
	v_pk_mul_f32 v[38:39], v[38:39], v[96:97] op_sel_hi:[1,0]
	v_pk_mul_f32 v[36:37], v[36:37], v[96:97] op_sel_hi:[1,0]
	v_pk_mul_f32 v[34:35], v[34:35], v[96:97] op_sel_hi:[1,0]
	v_pk_mul_f32 v[64:65], v[64:65], v[96:97] op_sel_hi:[1,0]
	v_pk_mul_f32 v[62:63], v[62:63], v[96:97] op_sel_hi:[1,0]
	v_pk_mul_f32 v[60:61], v[60:61], v[96:97] op_sel_hi:[1,0]
	v_pk_mul_f32 v[58:59], v[58:59], v[96:97] op_sel_hi:[1,0]
	v_pk_mul_f32 v[56:57], v[56:57], v[96:97] op_sel_hi:[1,0]
	v_pk_mul_f32 v[54:55], v[54:55], v[96:97] op_sel_hi:[1,0]
	v_pk_mul_f32 v[52:53], v[52:53], v[96:97] op_sel_hi:[1,0]
	v_pk_mul_f32 v[50:51], v[50:51], v[96:97] op_sel_hi:[1,0]
	v_pk_mul_f32 v[32:33], v[32:33], v[96:97] op_sel_hi:[1,0]
	v_pk_mul_f32 v[30:31], v[30:31], v[96:97] op_sel_hi:[1,0]
	v_pk_mul_f32 v[28:29], v[28:29], v[96:97] op_sel_hi:[1,0]
	v_pk_mul_f32 v[26:27], v[26:27], v[96:97] op_sel_hi:[1,0]
	v_pk_mul_f32 v[24:25], v[24:25], v[96:97] op_sel_hi:[1,0]
	v_pk_mul_f32 v[22:23], v[22:23], v[96:97] op_sel_hi:[1,0]
	v_pk_mul_f32 v[20:21], v[20:21], v[96:97] op_sel_hi:[1,0]
	v_pk_mul_f32 v[18:19], v[18:19], v[96:97] op_sel_hi:[1,0]
	v_pk_mul_f32 v[16:17], v[16:17], v[96:97] op_sel_hi:[1,0]
	v_pk_mul_f32 v[14:15], v[14:15], v[96:97] op_sel_hi:[1,0]
	v_pk_mul_f32 v[12:13], v[12:13], v[96:97] op_sel_hi:[1,0]
	v_pk_mul_f32 v[10:11], v[10:11], v[96:97] op_sel_hi:[1,0]
	v_pk_mul_f32 v[8:9], v[8:9], v[96:97] op_sel_hi:[1,0]
	v_pk_mul_f32 v[6:7], v[6:7], v[96:97] op_sel_hi:[1,0]
	v_pk_mul_f32 v[4:5], v[4:5], v[96:97] op_sel_hi:[1,0]
	v_pk_mul_f32 v[2:3], v[2:3], v[96:97] op_sel_hi:[1,0]
	v_mul_f32_e32 v242, v242, v96
	v_cvt_pk_bf16_f32 v177, v108, v97
	v_cvt_pk_bf16_f32 v190, v88, v103
	v_cvt_pk_bf16_f32 v191, v90, v105
	v_cvt_pk_bf16_f32 v192, v92, v107
	v_cvt_pk_bf16_f32 v193, v94, v110

.LBB0_225:
	s_and_b64 vcc, exec, s[26:27]
	s_cbranch_vccz .LBB0_239
	s_lshl_b32 s26, s33, 14
	s_add_i32 s26, s26, 0
	s_nop 1
	ds_read_b128 v[126:129], v249 offset:49152
	s_waitcnt lgkmcnt(1)
	v_mfma_f32_32x32x16_bf16 v[82:97], v[98:101], v[146:149], v[66:81]
	ds_read_b128 v[122:125], v102 offset:8192
	v_mfma_f32_32x32x16_bf16 v[98:113], v[114:117], v[146:149], v[66:81]
	v_add_u32_e32 v139, s26, v241
	ds_read_b128 v[114:117], v139
	v_mfma_f32_32x32x16_bf16 v[82:97], v[118:121], v[150:153], v[82:97]
	ds_read_b128 v[118:121], v139 offset:8192
	s_waitcnt lgkmcnt(0)
	v_mfma_f32_32x32x16_bf16 v[98:113], v[122:125], v[150:153], v[98:113]
	v_add_u32_e32 v139, s26, v243
	ds_read_b128 v[122:125], v139
	v_mfma_f32_32x32x16_bf16 v[82:97], v[114:117], v[154:157], v[82:97]
	ds_read_b128 v[114:117], v139 offset:8192
	v_mfma_f32_32x32x16_bf16 v[98:113], v[118:121], v[154:157], v[98:113]
	s_waitcnt lgkmcnt(0)
	v_mfma_f32_32x32x16_bf16 v[82:97], v[122:125], v[158:161], v[82:97]
	v_mfma_f32_32x32x16_bf16 v[98:113], v[114:117], v[158:161], v[98:113]
	s_nop 0
	ds_read_b128 v[122:125], v249 offset:53248
	ds_read_b128 v[118:121], v249 offset:57344
	ds_read_b128 v[114:117], v249 offset:61440
	s_add_i32 s26, s21, 0x80
	s_cmp_le_u32 s26, s20
	s_cbranch_scc1 .LBB0_228
	v_add_u32_e32 v130, s21, v248
	v_add_u32_e32 v130, 0x15f, v130
	v_and_b32_e32 v130, 0x3ffffffc, v130
	v_lshl_add_u32 v162, v130, 2, v0
	ds_read_b128 v[130:133], v162
	ds_read_b128 v[134:137], v162 offset:16
	ds_read_b128 v[138:141], v162 offset:64
	ds_read_b128 v[142:145], v162 offset:80
	s_waitcnt lgkmcnt(0)
	v_pk_add_f32 v[84:85], v[84:85], v[132:133]
	v_pk_add_f32 v[86:87], v[86:87], v[134:135]
	v_pk_add_f32 v[90:91], v[90:91], v[138:139]
	v_pk_add_f32 v[94:95], v[94:95], v[142:143]
	v_pk_add_f32 v[96:97], v[96:97], v[144:145]
	v_pk_add_f32 v[92:93], v[92:93], v[140:141]
	v_pk_add_f32 v[88:89], v[88:89], v[136:137]
	v_pk_add_f32 v[82:83], v[82:83], v[130:131]
	ds_read_b128 v[130:133], v162 offset:128
	ds_read_b128 v[134:137], v162 offset:144
	ds_read_b128 v[138:141], v162 offset:192
	ds_read_b128 v[142:145], v162 offset:208
	s_waitcnt lgkmcnt(0)
	v_pk_add_f32 v[100:101], v[100:101], v[132:133]
	v_pk_add_f32 v[102:103], v[102:103], v[134:135]
	v_pk_add_f32 v[106:107], v[106:107], v[138:139]
	v_pk_add_f32 v[110:111], v[110:111], v[142:143]
	v_pk_add_f32 v[112:113], v[112:113], v[144:145]
	v_pk_add_f32 v[108:109], v[108:109], v[140:141]
	v_pk_add_f32 v[104:105], v[104:105], v[136:137]
	v_pk_add_f32 v[98:99], v[98:99], v[130:131]
.LBB0_228:
	s_waitcnt lgkmcnt(3)
	v_mfma_f32_32x32x16_bf16 v[34:49], v[126:129], v[166:169], v[34:49]
	ds_read_b128 v[126:129], v212 offset:49152
	s_nop 0
	v_exp_f32_e32 v130, v82
	v_exp_f32_e32 v131, v83
	v_add_f32_e32 v132, v1, v130
	v_add_f32_e32 v133, v1, v131
	v_cvt_pk_bf16_f32 v162, v130, v131
	s_waitcnt lgkmcnt(3)
	v_mfma_f32_32x32x16_bf16 v[50:65], v[122:125], v[166:169], v[50:65]
	ds_read_b128 v[122:125], v212 offset:53248
	v_exp_f32_e32 v130, v84
	v_exp_f32_e32 v131, v85
	s_add_i32 s23, s23, 3
	s_cmp_le_u32 s23, s16
	v_add_f32_e32 v132, v132, v130
	v_add_f32_e32 v133, v133, v131
	v_cvt_pk_bf16_f32 v163, v130, v131
	s_cselect_b64 s[26:27], -1, 0
	s_cmp_gt_u32 s23, s16
	v_lshl_add_u64 v[130:131], s[8:9], 0, v[214:215]
	s_cbranch_scc1 .LBB0_230
	s_lshl_b32 s23, s48, 14
	v_lshl_add_u64 v[134:135], v[130:131], 0, s[50:51]
	s_add_i32 m0, s11, s23
	s_nop 0
	global_load_lds_dwordx4 v[134:135], off
.LBB0_230:
	s_waitcnt lgkmcnt(3)
	v_mfma_f32_32x32x16_bf16 v[18:33], v[118:121], v[166:169], v[18:33]
	ds_read_b128 v[118:121], v212 offset:57344
	v_exp_f32_e32 v134, v86
	v_exp_f32_e32 v135, v87
	v_add_f32_e32 v132, v132, v134
	v_add_f32_e32 v133, v133, v135
	v_cvt_pk_bf16_f32 v164, v134, v135
	s_waitcnt lgkmcnt(3)
	v_mfma_f32_32x32x16_bf16 v[2:17], v[114:117], v[166:169], v[2:17]
	ds_read_b128 v[114:117], v212 offset:61440
	v_exp_f32_e32 v134, v88
	v_exp_f32_e32 v135, v89
	v_add_f32_e32 v136, v132, v134
	v_add_f32_e32 v133, v133, v135
	v_cvt_pk_bf16_f32 v165, v134, v135
	s_waitcnt lgkmcnt(3)
	v_mfma_f32_32x32x16_bf16 v[34:49], v[126:129], v[174:177], v[34:49]
	v_add_u32_e32 v132, s54, v246
	ds_read_b128 v[126:129], v132 offset:49152
	v_exp_f32_e32 v134, v90
	v_exp_f32_e32 v135, v91
	v_add_f32_e32 v136, v136, v134
	v_add_f32_e32 v137, v133, v135
	v_cvt_pk_bf16_f32 v170, v134, v135
	s_waitcnt lgkmcnt(3)
	v_mfma_f32_32x32x16_bf16 v[50:65], v[122:125], v[174:177], v[50:65]
	ds_read_b128 v[122:125], v132 offset:53248
	v_exp_f32_e32 v135, v92
	v_exp_f32_e32 v138, v93
	v_add_f32_e32 v133, v136, v135
	v_add_f32_e32 v134, v137, v138
	s_andn2_b64 vcc, exec, s[26:27]
	v_cvt_pk_bf16_f32 v171, v135, v138
	s_cbranch_vccnz .LBB0_232
	s_lshl_b32 s23, s48, 14
	s_add_i32 s23, s11, s23
	v_lshl_add_u64 v[130:131], v[130:131], 0, s[4:5]
	s_add_i32 m0, s23, 0x2000
	s_nop 0
	global_load_lds_dwordx4 v[130:131], off
.LBB0_232:
	s_waitcnt lgkmcnt(3)
	v_mfma_f32_32x32x16_bf16 v[18:33], v[118:121], v[174:177], v[18:33]
	ds_read_b128 v[118:121], v132 offset:57344
	v_exp_f32_e32 v130, v94
	v_exp_f32_e32 v131, v95
	v_add_f32_e32 v133, v133, v130
	v_add_f32_e32 v134, v134, v131
	v_cvt_pk_bf16_f32 v172, v130, v131
	s_waitcnt lgkmcnt(3)
	v_mfma_f32_32x32x16_bf16 v[2:17], v[114:117], v[174:177], v[2:17]
	ds_read_b128 v[114:117], v132 offset:61440
	v_exp_f32_e32 v130, v96
	v_exp_f32_e32 v131, v97
	v_add_f32_e32 v133, v133, v130
	v_add_f32_e32 v134, v134, v131
	v_cvt_pk_bf16_f32 v173, v130, v131
	s_waitcnt lgkmcnt(3)
	v_mfma_f32_32x32x16_bf16 v[34:49], v[126:129], v[182:185], v[34:49]
	v_add_u32_e32 v132, s54, v247
	ds_read_b128 v[126:129], v132 offset:49152
	v_exp_f32_e32 v130, v98
	v_exp_f32_e32 v131, v99
	v_add_f32_e32 v133, v133, v130
	v_add_f32_e32 v134, v134, v131
	v_cvt_pk_bf16_f32 v178, v130, v131
	s_waitcnt lgkmcnt(3)
	v_mfma_f32_32x32x16_bf16 v[50:65], v[122:125], v[182:185], v[50:65]
	v_exp_f32_e32 v130, v100
	v_exp_f32_e32 v131, v101
	ds_read_b128 v[122:125], v132 offset:53248
	v_add_f32_e32 v133, v133, v130
	v_add_f32_e32 v134, v134, v131
	v_cvt_pk_bf16_f32 v179, v130, v131
	v_cndmask_b32_e64 v130, 0, 1, s[88:89]
	v_cmp_ne_u32_e64 s[40:41], 1, v130
	s_andn2_b64 vcc, exec, s[88:89]
	v_lshl_add_u64 v[130:131], s[8:9], 0, v[216:217]
	s_cbranch_vccnz .LBB0_234
	s_lshl_b32 s23, s31, 14
	s_add_i32 s23, s11, s23
	s_add_i32 m0, s23, 0xc000
	s_add_u32 s100, s8, s0
	s_addc_u32 s101, s9, s1
	global_load_lds_dwordx4 v216, s[100:101]
.LBB0_234:
	s_waitcnt lgkmcnt(3)
	v_mfma_f32_32x32x16_bf16 v[18:33], v[118:121], v[182:185], v[18:33]
	ds_read_b128 v[118:121], v132 offset:57344
	v_exp_f32_e32 v135, v102
	v_exp_f32_e32 v136, v103
	v_add_f32_e32 v133, v133, v135
	v_add_f32_e32 v134, v134, v136
	v_cvt_pk_bf16_f32 v180, v135, v136
	s_waitcnt lgkmcnt(3)
	v_mfma_f32_32x32x16_bf16 v[2:17], v[114:117], v[182:185], v[2:17]
	ds_read_b128 v[114:117], v132 offset:61440
	v_exp_f32_e32 v132, v104
	v_exp_f32_e32 v135, v105
	v_add_f32_e32 v133, v133, v132
	v_add_f32_e32 v134, v134, v135
	v_cvt_pk_bf16_f32 v181, v132, v135
	s_waitcnt lgkmcnt(3)
	v_mfma_f32_32x32x16_bf16 v[34:49], v[126:129], v[190:193], v[34:49]
	v_exp_f32_e32 v126, v106
	v_exp_f32_e32 v127, v107
	v_add_f32_e32 v128, v133, v126
	v_add_f32_e32 v129, v134, v127
	v_cvt_pk_bf16_f32 v186, v126, v127
	s_waitcnt lgkmcnt(2)
	v_mfma_f32_32x32x16_bf16 v[50:65], v[122:125], v[190:193], v[50:65]
	v_exp_f32_e32 v124, v108
	v_exp_f32_e32 v125, v109
	v_add_f32_e32 v122, v128, v124
	v_add_f32_e32 v123, v129, v125
	s_and_b64 vcc, exec, s[40:41]
	v_cvt_pk_bf16_f32 v187, v124, v125
	s_cbranch_vccnz .LBB0_236
	s_lshl_b32 s23, s31, 14
	s_add_i32 s23, s11, s23
	v_lshl_add_u64 v[124:125], v[130:131], 0, s[52:53]
	s_add_i32 m0, s23, 0xe000
	s_nop 0
	global_load_lds_dwordx4 v[124:125], off
.LBB0_236:
	s_waitcnt lgkmcnt(1)
	v_mfma_f32_32x32x16_bf16 v[18:33], v[118:121], v[190:193], v[18:33]
	v_exp_f32_e32 v118, v110
	v_exp_f32_e32 v119, v111
	v_add_f32_e32 v120, v122, v118
	v_add_f32_e32 v121, v123, v119
	v_cvt_pk_bf16_f32 v188, v118, v119
	s_waitcnt lgkmcnt(0)
	v_mfma_f32_32x32x16_bf16 v[2:17], v[114:117], v[190:193], v[2:17]
	v_exp_f32_e32 v114, v112
	v_exp_f32_e32 v115, v113
	v_add_f32_e32 v116, v120, v114
	v_add_f32_e32 v117, v121, v115
	v_cvt_pk_bf16_f32 v189, v114, v115
	v_add_f32_e32 v212, v116, v117
	v_cmp_nge_f32_e32 vcc, s7, v212
	s_cbranch_vccz .LBB0_238
	v_max_f32_e32 v66, v99, v99
	v_max_f32_e32 v67, v83, v83
	v_max_f32_e32 v66, v67, v66
	v_max3_f32 v66, v82, v98, v66
	v_max3_f32 v67, v100, v85, v101
	v_max3_f32 v66, v66, v84, v67
	v_max3_f32 v67, v102, v87, v103
	v_max3_f32 v66, v66, v86, v67
	v_max3_f32 v67, v104, v89, v105
	v_max3_f32 v66, v66, v88, v67
	v_max3_f32 v67, v106, v91, v107
	v_max3_f32 v66, v66, v90, v67
	v_max3_f32 v67, v108, v93, v109
	v_max3_f32 v66, v66, v92, v67
	v_max3_f32 v67, v110, v95, v111
	v_max3_f32 v66, v66, v94, v67
	v_max3_f32 v67, v112, v97, v113
	v_max3_f32 v66, v66, v96, v67
	v_mov_b32_e32 v67, v66
	s_nop 1
	v_permlane32_swap_b32_e32 v66, v67
	v_max_f32_e32 v67, v67, v67
	v_max_f32_e32 v66, v66, v66
	v_max_f32_e32 v66, v66, v67
	v_cmp_lt_f32_e32 vcc, s57, v66
	s_nop 1
	v_cndmask_b32_e32 v68, 0, v66, vcc
	v_sub_f32_e32 v66, v82, v68
	v_exp_f32_e32 v116, v66
	v_sub_f32_e32 v66, v98, v68
	v_exp_f32_e32 v117, v66
	v_sub_f32_e32 v66, v83, v68
	v_exp_f32_e32 v118, v66
	v_sub_f32_e32 v66, v99, v68
	v_exp_f32_e32 v119, v66
	v_sub_f32_e32 v66, v84, v68
	v_exp_f32_e32 v114, v66
	v_sub_f32_e32 v66, v100, v68
	v_exp_f32_e32 v82, v66
	v_add_f32_e32 v66, v116, v117
	v_add_f32_e32 v83, 0, v66
	v_add_f32_e32 v115, v118, v119
	v_pk_add_f32 v[66:67], v[114:115], v[82:83]
	v_cvt_pk_bf16_f32 v162, v116, v118
	v_pk_add_f32 v[98:99], v[66:67], v[66:67] op_sel_hi:[0,1]
	v_sub_f32_e32 v66, v85, v68
	v_exp_f32_e32 v83, v66
	v_sub_f32_e32 v66, v101, v68
	v_exp_f32_e32 v115, v66
	v_sub_f32_e32 v66, v86, v68
	v_exp_f32_e32 v100, v66
	v_sub_f32_e32 v66, v102, v68
	v_exp_f32_e32 v98, v66
	v_add_f32_e32 v101, v83, v115
	v_cvt_pk_bf16_f32 v163, v114, v83
	v_cvt_pk_bf16_f32 v178, v117, v119
	v_pk_add_f32 v[66:67], v[100:101], v[98:99]
	v_cvt_pk_bf16_f32 v179, v82, v115
	v_pk_add_f32 v[84:85], v[66:67], v[66:67] op_sel_hi:[0,1]
	v_sub_f32_e32 v66, v87, v68
	v_exp_f32_e32 v99, v66
	v_sub_f32_e32 v66, v103, v68
	v_exp_f32_e32 v101, v66
	v_sub_f32_e32 v66, v88, v68
	v_exp_f32_e32 v102, v66
	v_sub_f32_e32 v66, v104, v68
	v_exp_f32_e32 v84, v66
	v_add_f32_e32 v103, v99, v101
	v_cvt_pk_bf16_f32 v164, v100, v99
	v_cvt_pk_bf16_f32 v180, v98, v101
	v_pk_add_f32 v[66:67], v[102:103], v[84:85]
	s_nop 0
	v_pk_add_f32 v[86:87], v[66:67], v[66:67] op_sel_hi:[0,1]
	v_sub_f32_e32 v66, v89, v68
	v_exp_f32_e32 v85, v66
	v_sub_f32_e32 v66, v105, v68
	v_exp_f32_e32 v103, v66
	v_sub_f32_e32 v66, v90, v68
	v_exp_f32_e32 v104, v66
	v_sub_f32_e32 v66, v106, v68
	v_exp_f32_e32 v86, v66
	v_add_f32_e32 v105, v85, v103
	v_cvt_pk_bf16_f32 v165, v102, v85
	v_cvt_pk_bf16_f32 v181, v84, v103
	v_pk_add_f32 v[66:67], v[104:105], v[86:87]
	s_nop 0
	v_pk_add_f32 v[88:89], v[66:67], v[66:67] op_sel_hi:[0,1]
	v_sub_f32_e32 v66, v91, v68
	v_exp_f32_e32 v87, v66
	v_sub_f32_e32 v66, v107, v68
	v_exp_f32_e32 v105, v66
	v_sub_f32_e32 v66, v92, v68
	v_exp_f32_e32 v90, v66
	v_sub_f32_e32 v66, v108, v68
	v_exp_f32_e32 v88, v66
	v_sub_f32_e32 v66, v97, v68
	v_add_f32_e32 v91, v87, v105
	v_exp_f32_e32 v97, v66
	v_pk_add_f32 v[66:67], v[90:91], v[88:89]
	v_cvt_pk_bf16_f32 v170, v104, v87
	v_pk_add_f32 v[106:107], v[66:67], v[66:67] op_sel_hi:[0,1]
	v_sub_f32_e32 v66, v93, v68
	v_exp_f32_e32 v89, v66
	v_sub_f32_e32 v66, v109, v68
	v_exp_f32_e32 v91, v66
	v_sub_f32_e32 v66, v94, v68
	v_exp_f32_e32 v92, v66
	v_sub_f32_e32 v66, v110, v68
	v_exp_f32_e32 v106, v66
	v_sub_f32_e32 v66, v113, v68
	v_add_f32_e32 v93, v89, v91
	v_exp_f32_e32 v110, v66
	v_pk_add_f32 v[66:67], v[92:93], v[106:107]
	v_cvt_pk_bf16_f32 v171, v90, v89
	v_pk_add_f32 v[108:109], v[66:67], v[66:67] op_sel_hi:[0,1]
	v_sub_f32_e32 v66, v95, v68
	v_exp_f32_e32 v93, v66
	v_sub_f32_e32 v66, v111, v68
	v_exp_f32_e32 v107, v66
	v_sub_f32_e32 v66, v96, v68
	v_exp_f32_e32 v94, v66
	v_sub_f32_e32 v66, v112, v68
	v_exp_f32_e32 v108, v66
	v_add_f32_e32 v95, v93, v107
	v_exp_f32_e64 v96, -v68
	v_add_f32_e32 v212, v97, v110
	v_pk_add_f32 v[66:67], v[94:95], v[108:109]
	v_cvt_pk_bf16_f32 v172, v92, v93
	v_pk_add_f32 v[66:67], v[66:67], v[66:67] op_sel:[0,1] op_sel_hi:[1,0]
	v_pk_mul_f32 v[48:49], v[48:49], v[96:97] op_sel_hi:[1,0]
	v_mov_b32_e32 v67, v68
	v_pk_add_f32 v[212:213], v[212:213], v[66:67]
	v_pk_mul_f32 v[46:47], v[46:47], v[96:97] op_sel_hi:[1,0]
	v_xor_b32_e32 v66, 0x80000000, v213
	v_mov_b32_e32 v67, v66
	v_mov_b32_e32 v68, v66
	v_mov_b32_e32 v69, v66
	v_mov_b32_e32 v70, v66
	v_mov_b32_e32 v71, v66
	v_mov_b32_e32 v72, v66
	v_mov_b32_e32 v73, v66
	v_mov_b32_e32 v74, v66
	v_mov_b32_e32 v75, v66
	v_mov_b32_e32 v76, v66
	v_mov_b32_e32 v77, v66
	v_mov_b32_e32 v78, v66
	v_mov_b32_e32 v79, v66
	v_mov_b32_e32 v80, v66
	v_mov_b32_e32 v81, v66
	v_pk_mul_f32 v[44:45], v[44:45], v[96:97] op_sel_hi:[1,0]
	v_pk_mul_f32 v[42:43], v[42:43], v[96:97] op_sel_hi:[1,0]
	v_pk_mul_f32 v[40:41], v[40:41], v[96:97] op_sel_hi:[1,0]
	v_pk_mul_f32 v[38:39], v[38:39], v[96:97] op_sel_hi:[1,0]
	v_pk_mul_f32 v[36:37], v[36:37], v[96:97] op_sel_hi:[1,0]
	v_pk_mul_f32 v[34:35], v[34:35], v[96:97] op_sel_hi:[1,0]
	v_pk_mul_f32 v[64:65], v[64:65], v[96:97] op_sel_hi:[1,0]
	v_pk_mul_f32 v[62:63], v[62:63], v[96:97] op_sel_hi:[1,0]
	v_pk_mul_f32 v[60:61], v[60:61], v[96:97] op_sel_hi:[1,0]
	v_pk_mul_f32 v[58:59], v[58:59], v[96:97] op_sel_hi:[1,0]
	v_pk_mul_f32 v[56:57], v[56:57], v[96:97] op_sel_hi:[1,0]
	v_pk_mul_f32 v[54:55], v[54:55], v[96:97] op_sel_hi:[1,0]
	v_pk_mul_f32 v[52:53], v[52:53], v[96:97] op_sel_hi:[1,0]
	v_pk_mul_f32 v[50:51], v[50:51], v[96:97] op_sel_hi:[1,0]
	v_pk_mul_f32 v[32:33], v[32:33], v[96:97] op_sel_hi:[1,0]
	v_pk_mul_f32 v[30:31], v[30:31], v[96:97] op_sel_hi:[1,0]
	v_pk_mul_f32 v[28:29], v[28:29], v[96:97] op_sel_hi:[1,0]
	v_pk_mul_f32 v[26:27], v[26:27], v[96:97] op_sel_hi:[1,0]
	v_pk_mul_f32 v[24:25], v[24:25], v[96:97] op_sel_hi:[1,0]
	v_pk_mul_f32 v[22:23], v[22:23], v[96:97] op_sel_hi:[1,0]
	v_pk_mul_f32 v[20:21], v[20:21], v[96:97] op_sel_hi:[1,0]
	v_pk_mul_f32 v[18:19], v[18:19], v[96:97] op_sel_hi:[1,0]
	v_pk_mul_f32 v[16:17], v[16:17], v[96:97] op_sel_hi:[1,0]
	v_pk_mul_f32 v[14:15], v[14:15], v[96:97] op_sel_hi:[1,0]
	v_pk_mul_f32 v[12:13], v[12:13], v[96:97] op_sel_hi:[1,0]
	v_pk_mul_f32 v[10:11], v[10:11], v[96:97] op_sel_hi:[1,0]
	v_pk_mul_f32 v[8:9], v[8:9], v[96:97] op_sel_hi:[1,0]
	v_pk_mul_f32 v[6:7], v[6:7], v[96:97] op_sel_hi:[1,0]
	v_pk_mul_f32 v[4:5], v[4:5], v[96:97] op_sel_hi:[1,0]
	v_pk_mul_f32 v[2:3], v[2:3], v[96:97] op_sel_hi:[1,0]
	v_mul_f32_e32 v242, v242, v96
	v_cvt_pk_bf16_f32 v173, v94, v97
	v_cvt_pk_bf16_f32 v186, v86, v105
	v_cvt_pk_bf16_f32 v187, v88, v91
	v_cvt_pk_bf16_f32 v188, v106, v107
	v_cvt_pk_bf16_f32 v189, v108, v110

.LBB0_288:
	s_and_b64 vcc, exec, s[26:27]
	s_cbranch_vccz .LBB0_302
	s_lshl_b32 s21, s31, 14
	s_add_i32 s21, s21, 0
	s_nop 1
	ds_read_b128 v[126:129], v212 offset:49152
	s_waitcnt lgkmcnt(1)
	v_mfma_f32_32x32x16_bf16 v[82:97], v[98:101], v[146:149], v[66:81]
	ds_read_b128 v[122:125], v102 offset:8192
	v_mfma_f32_32x32x16_bf16 v[98:113], v[114:117], v[146:149], v[66:81]
	v_add_u32_e32 v139, s21, v241
	ds_read_b128 v[114:117], v139
	v_mfma_f32_32x32x16_bf16 v[82:97], v[118:121], v[150:153], v[82:97]
	ds_read_b128 v[118:121], v139 offset:8192
	s_waitcnt lgkmcnt(0)
	v_mfma_f32_32x32x16_bf16 v[98:113], v[122:125], v[150:153], v[98:113]
	v_add_u32_e32 v139, s21, v242
	ds_read_b128 v[122:125], v139
	v_mfma_f32_32x32x16_bf16 v[82:97], v[114:117], v[154:157], v[82:97]
	ds_read_b128 v[114:117], v139 offset:8192
	v_mfma_f32_32x32x16_bf16 v[98:113], v[118:121], v[154:157], v[98:113]
	s_waitcnt lgkmcnt(0)
	v_mfma_f32_32x32x16_bf16 v[82:97], v[122:125], v[158:161], v[82:97]
	v_mfma_f32_32x32x16_bf16 v[98:113], v[114:117], v[158:161], v[98:113]
	s_nop 0
	ds_read_b128 v[122:125], v212 offset:53248
	ds_read_b128 v[118:121], v212 offset:57344
	ds_read_b128 v[114:117], v212 offset:61440
	s_cmp_le_u32 s20, s16
	s_cbranch_scc1 .LBB0_291
	v_add3_u32 v130, v249, s20, 47
	v_and_b32_e32 v130, 0x3ffffffc, v130
	v_lshl_add_u32 v166, v130, 2, v244
	ds_read_b128 v[130:133], v166
	ds_read_b128 v[134:137], v166 offset:16
	ds_read_b128 v[138:141], v166 offset:64
	ds_read_b128 v[142:145], v166 offset:80
	s_waitcnt lgkmcnt(0)
	v_pk_add_f32 v[84:85], v[84:85], v[132:133]
	v_pk_add_f32 v[88:89], v[88:89], v[136:137]
	v_pk_add_f32 v[92:93], v[92:93], v[140:141]
	v_pk_add_f32 v[96:97], v[96:97], v[144:145]
	v_pk_add_f32 v[94:95], v[94:95], v[142:143]
	v_pk_add_f32 v[90:91], v[90:91], v[138:139]
	v_pk_add_f32 v[86:87], v[86:87], v[134:135]
	v_pk_add_f32 v[82:83], v[82:83], v[130:131]
	ds_read_b128 v[130:133], v166 offset:128
	ds_read_b128 v[134:137], v166 offset:144
	ds_read_b128 v[138:141], v166 offset:192
	ds_read_b128 v[142:145], v166 offset:208
	s_waitcnt lgkmcnt(0)
	v_pk_add_f32 v[100:101], v[100:101], v[132:133]
	v_pk_add_f32 v[104:105], v[104:105], v[136:137]
	v_pk_add_f32 v[108:109], v[108:109], v[140:141]
	v_pk_add_f32 v[112:113], v[112:113], v[144:145]
	v_pk_add_f32 v[110:111], v[110:111], v[142:143]
	v_pk_add_f32 v[106:107], v[106:107], v[138:139]
	v_pk_add_f32 v[102:103], v[102:103], v[134:135]
	v_pk_add_f32 v[98:99], v[98:99], v[130:131]
.LBB0_291:
	s_waitcnt lgkmcnt(3)
	v_mfma_f32_32x32x16_bf16 v[50:65], v[126:129], v[162:165], v[50:65]
	ds_read_b128 v[126:129], v0 offset:49152
	s_nop 1
	v_exp_f32_e32 v130, v82
	v_exp_f32_e32 v131, v83
	v_add_f32_e32 v132, v1, v130
	v_add_f32_e32 v133, v1, v131
	v_cvt_pk_bf16_f32 v166, v130, v131
	s_waitcnt lgkmcnt(3)
	v_mfma_f32_32x32x16_bf16 v[34:49], v[122:125], v[162:165], v[34:49]
	ds_read_b128 v[122:125], v0 offset:53248
	v_exp_f32_e32 v134, v84
	v_exp_f32_e32 v135, v85
	s_add_i32 s21, s22, 2
	s_cmp_lt_u32 s21, s18
	v_add_f32_e32 v130, v132, v134
	v_add_f32_e32 v131, v133, v135
	v_cvt_pk_bf16_f32 v167, v134, v135
	s_cselect_b64 s[26:27], -1, 0
	s_cmp_ge_u32 s21, s18
	s_cbranch_scc1 .LBB0_293
	s_lshl_b32 s37, s28, 14
	s_add_i32 m0, s10, s37
	s_add_u32 s100, s8, s80
	s_addc_u32 s101, s9, s81
	global_load_lds_dwordx4 v214, s[100:101]
.LBB0_293:
	s_waitcnt lgkmcnt(3)
	v_mfma_f32_32x32x16_bf16 v[18:33], v[118:121], v[162:165], v[18:33]
	ds_read_b128 v[118:121], v0 offset:57344
	v_exp_f32_e32 v132, v86
	v_exp_f32_e32 v133, v87
	v_add_f32_e32 v130, v130, v132
	v_add_f32_e32 v131, v131, v133
	v_cvt_pk_bf16_f32 v168, v132, v133
	s_waitcnt lgkmcnt(3)
	v_mfma_f32_32x32x16_bf16 v[2:17], v[114:117], v[162:165], v[2:17]
	ds_read_b128 v[114:117], v0 offset:61440
	v_exp_f32_e32 v0, v88
	v_exp_f32_e32 v132, v89
	v_add_f32_e32 v130, v130, v0
	v_add_f32_e32 v131, v131, v132
	v_cvt_pk_bf16_f32 v169, v0, v132
	s_waitcnt lgkmcnt(3)
	v_mfma_f32_32x32x16_bf16 v[50:65], v[126:129], v[170:173], v[50:65]
	v_add_u32_e32 v0, s36, v247
	ds_read_b128 v[126:129], v0 offset:49152
	v_exp_f32_e32 v132, v90
	v_exp_f32_e32 v133, v91
	v_add_f32_e32 v130, v130, v132
	v_add_f32_e32 v131, v131, v133
	v_cvt_pk_bf16_f32 v174, v132, v133
	s_waitcnt lgkmcnt(3)
	v_mfma_f32_32x32x16_bf16 v[34:49], v[122:125], v[170:173], v[34:49]
	ds_read_b128 v[122:125], v0 offset:53248
	v_exp_f32_e32 v132, v92
	v_exp_f32_e32 v133, v93
	v_add_f32_e32 v130, v130, v132
	v_add_f32_e32 v131, v131, v133
	s_andn2_b64 vcc, exec, s[26:27]
	v_cvt_pk_bf16_f32 v175, v132, v133
	s_cbranch_vccnz .LBB0_295
	s_lshl_b32 s26, s28, 14
	s_add_i32 s26, s10, s26
	s_add_i32 m0, s26, 0x2000
	s_add_u32 s100, s8, s62
	s_addc_u32 s101, s9, s63
	global_load_lds_dwordx4 v214, s[100:101]
.LBB0_295:
	s_waitcnt lgkmcnt(3)
	v_mfma_f32_32x32x16_bf16 v[18:33], v[118:121], v[170:173], v[18:33]
	ds_read_b128 v[118:121], v0 offset:57344
	v_exp_f32_e32 v132, v94
	v_exp_f32_e32 v133, v95
	v_add_f32_e32 v130, v130, v132
	v_add_f32_e32 v131, v131, v133
	v_cvt_pk_bf16_f32 v176, v132, v133
	s_waitcnt lgkmcnt(3)
	v_mfma_f32_32x32x16_bf16 v[2:17], v[114:117], v[170:173], v[2:17]
	ds_read_b128 v[114:117], v0 offset:61440
	v_exp_f32_e32 v0, v96
	v_exp_f32_e32 v132, v97
	v_add_f32_e32 v130, v130, v0
	v_add_f32_e32 v131, v131, v132
	v_cvt_pk_bf16_f32 v177, v0, v132
	s_waitcnt lgkmcnt(3)
	v_mfma_f32_32x32x16_bf16 v[50:65], v[126:129], v[178:181], v[50:65]
	v_add_u32_e32 v0, s36, v248
	ds_read_b128 v[126:129], v0 offset:49152
	v_exp_f32_e32 v132, v98
	v_exp_f32_e32 v133, v99
	v_add_f32_e32 v130, v130, v132
	v_add_f32_e32 v131, v131, v133
	v_cvt_pk_bf16_f32 v182, v132, v133
	s_waitcnt lgkmcnt(3)
	v_mfma_f32_32x32x16_bf16 v[34:49], v[122:125], v[178:181], v[34:49]
	v_exp_f32_e32 v132, v100
	v_exp_f32_e32 v133, v101
	ds_read_b128 v[122:125], v0 offset:53248
	v_add_f32_e32 v130, v130, v132
	v_add_f32_e32 v131, v131, v133
	v_cvt_pk_bf16_f32 v183, v132, v133
	v_cndmask_b32_e64 v132, 0, 1, s[44:45]
	v_cmp_ne_u32_e64 s[40:41], 1, v132
	s_andn2_b64 vcc, exec, s[44:45]
	s_cbranch_vccnz .LBB0_297
	s_lshl_b32 s26, s23, 14
	s_add_i32 s26, s10, s26
	s_add_i32 m0, s26, 0xc000
	s_add_u32 s100, s8, s96
	s_addc_u32 s101, s9, s97
	global_load_lds_dwordx4 v216, s[100:101]
.LBB0_297:
	s_waitcnt lgkmcnt(3)
	v_mfma_f32_32x32x16_bf16 v[18:33], v[118:121], v[178:181], v[18:33]
	ds_read_b128 v[118:121], v0 offset:57344
	v_exp_f32_e32 v132, v102
	v_exp_f32_e32 v133, v103
	v_add_f32_e32 v130, v130, v132
	v_add_f32_e32 v131, v131, v133
	v_cvt_pk_bf16_f32 v184, v132, v133
	s_waitcnt lgkmcnt(3)
	v_mfma_f32_32x32x16_bf16 v[2:17], v[114:117], v[178:181], v[2:17]
	ds_read_b128 v[114:117], v0 offset:61440
	v_exp_f32_e32 v0, v104
	v_exp_f32_e32 v132, v105
	v_add_f32_e32 v130, v130, v0
	v_add_f32_e32 v131, v131, v132
	v_cvt_pk_bf16_f32 v185, v0, v132
	s_waitcnt lgkmcnt(3)
	v_mfma_f32_32x32x16_bf16 v[50:65], v[126:129], v[186:189], v[50:65]
	v_exp_f32_e32 v0, v106
	v_exp_f32_e32 v126, v107
	v_add_f32_e32 v127, v130, v0
	v_add_f32_e32 v128, v131, v126
	v_cvt_pk_bf16_f32 v190, v0, v126
	s_waitcnt lgkmcnt(2)
	v_mfma_f32_32x32x16_bf16 v[34:49], v[122:125], v[186:189], v[34:49]
	v_exp_f32_e32 v123, v108
	v_exp_f32_e32 v124, v109
	v_add_f32_e32 v0, v127, v123
	v_add_f32_e32 v122, v128, v124
	s_and_b64 vcc, exec, s[40:41]
	v_cvt_pk_bf16_f32 v191, v123, v124
	s_cbranch_vccnz .LBB0_299
	s_lshl_b32 s26, s23, 14
	s_add_i32 s26, s10, s26
	s_add_i32 m0, s26, 0xe000
	s_add_u32 s100, s8, s58
	s_addc_u32 s101, s9, s59
	global_load_lds_dwordx4 v216, s[100:101]
.LBB0_299:
	s_waitcnt lgkmcnt(1)
	v_mfma_f32_32x32x16_bf16 v[18:33], v[118:121], v[186:189], v[18:33]
	v_exp_f32_e32 v118, v110
	v_exp_f32_e32 v119, v111
	v_add_f32_e32 v0, v0, v118
	v_add_f32_e32 v120, v122, v119
	v_cvt_pk_bf16_f32 v192, v118, v119
	s_waitcnt lgkmcnt(0)
	v_mfma_f32_32x32x16_bf16 v[2:17], v[114:117], v[186:189], v[2:17]
	v_exp_f32_e32 v114, v112
	v_exp_f32_e32 v115, v113
	v_add_f32_e32 v0, v0, v114
	v_add_f32_e32 v116, v120, v115
	v_cvt_pk_bf16_f32 v193, v114, v115
	v_add_f32_e32 v212, v0, v116
	v_cmp_nge_f32_e32 vcc, s7, v212
	s_cbranch_vccz .LBB0_301
	v_max_f32_e32 v0, v99, v99
	v_max_f32_e32 v66, v83, v83
	v_max_f32_e32 v0, v66, v0
	v_max3_f32 v0, v82, v98, v0
	v_max3_f32 v66, v100, v85, v101
	v_max3_f32 v0, v0, v84, v66
	v_max3_f32 v66, v102, v87, v103
	v_max3_f32 v0, v0, v86, v66
	v_max3_f32 v66, v104, v89, v105
	v_max3_f32 v0, v0, v88, v66
	v_max3_f32 v66, v106, v91, v107
	v_max3_f32 v0, v0, v90, v66
	v_max3_f32 v66, v108, v93, v109
	v_max3_f32 v0, v0, v92, v66
	v_max3_f32 v66, v110, v95, v111
	v_max3_f32 v0, v0, v94, v66
	v_max3_f32 v66, v112, v97, v113
	v_max3_f32 v0, v0, v96, v66
	v_mov_b32_e32 v66, v0
	s_nop 1
	v_permlane32_swap_b32_e32 v0, v66
	v_max_f32_e32 v66, v66, v66
	v_max_f32_e32 v0, v0, v0
	v_max_f32_e32 v0, v0, v66
	v_cmp_lt_f32_e32 vcc, s57, v0
	s_nop 1
	v_cndmask_b32_e32 v68, 0, v0, vcc
	v_sub_f32_e32 v0, v82, v68
	v_exp_f32_e32 v116, v0
	v_sub_f32_e32 v0, v98, v68
	v_exp_f32_e32 v117, v0
	v_sub_f32_e32 v0, v83, v68
	v_exp_f32_e32 v118, v0
	v_sub_f32_e32 v0, v99, v68
	v_exp_f32_e32 v119, v0
	v_sub_f32_e32 v0, v84, v68
	v_exp_f32_e32 v98, v0
	v_sub_f32_e32 v0, v100, v68
	v_exp_f32_e32 v82, v0
	v_add_f32_e32 v0, v117, v116
	v_add_f32_e32 v99, 0, v0
	v_add_f32_e32 v83, v119, v118
	v_sub_f32_e32 v0, v85, v68
	v_pk_add_f32 v[66:67], v[82:83], v[98:99]
	v_exp_f32_e32 v83, v0
	v_sub_f32_e32 v0, v101, v68
	v_pk_add_f32 v[114:115], v[66:67], v[66:67] op_sel_hi:[0,1]
	v_exp_f32_e32 v99, v0
	v_sub_f32_e32 v0, v86, v68
	v_exp_f32_e32 v114, v0
	v_sub_f32_e32 v0, v102, v68
	v_exp_f32_e32 v84, v0
	v_add_f32_e32 v85, v99, v83
	v_sub_f32_e32 v0, v87, v68
	v_cvt_pk_bf16_f32 v166, v116, v118
	v_pk_add_f32 v[66:67], v[84:85], v[114:115]
	v_exp_f32_e32 v85, v0
	v_sub_f32_e32 v0, v103, v68
	v_pk_add_f32 v[100:101], v[66:67], v[66:67] op_sel_hi:[0,1]
	v_exp_f32_e32 v115, v0
	v_sub_f32_e32 v0, v88, v68
	v_exp_f32_e32 v100, v0
	v_sub_f32_e32 v0, v104, v68
	v_exp_f32_e32 v86, v0
	v_add_f32_e32 v87, v115, v85
	v_sub_f32_e32 v0, v89, v68
	v_cvt_pk_bf16_f32 v167, v98, v83
	v_pk_add_f32 v[66:67], v[86:87], v[100:101]
	v_exp_f32_e32 v87, v0
	v_sub_f32_e32 v0, v105, v68
	v_pk_add_f32 v[102:103], v[66:67], v[66:67] op_sel_hi:[0,1]
	v_exp_f32_e32 v101, v0
	v_sub_f32_e32 v0, v90, v68
	v_exp_f32_e32 v102, v0
	v_sub_f32_e32 v0, v106, v68
	v_exp_f32_e32 v88, v0
	v_add_f32_e32 v89, v101, v87
	v_sub_f32_e32 v0, v91, v68
	v_cvt_pk_bf16_f32 v168, v114, v85
	v_pk_add_f32 v[66:67], v[88:89], v[102:103]
	v_exp_f32_e32 v89, v0
	v_sub_f32_e32 v0, v107, v68
	v_pk_add_f32 v[104:105], v[66:67], v[66:67] op_sel_hi:[0,1]
	v_exp_f32_e32 v103, v0
	v_sub_f32_e32 v0, v92, v68
	v_exp_f32_e32 v104, v0
	v_sub_f32_e32 v0, v108, v68
	v_exp_f32_e32 v90, v0
	v_sub_f32_e32 v0, v97, v68
	v_exp_f32_e32 v97, v0
	v_add_f32_e32 v91, v103, v89
	v_sub_f32_e32 v0, v93, v68
	v_pk_add_f32 v[66:67], v[90:91], v[104:105]
	v_exp_f32_e32 v91, v0
	v_sub_f32_e32 v0, v109, v68
	v_pk_add_f32 v[106:107], v[66:67], v[66:67] op_sel_hi:[0,1]
	v_exp_f32_e32 v105, v0
	v_sub_f32_e32 v0, v94, v68
	v_exp_f32_e32 v106, v0
	v_sub_f32_e32 v0, v110, v68
	v_exp_f32_e32 v92, v0
	v_sub_f32_e32 v0, v113, v68
	v_exp_f32_e32 v110, v0
	v_add_f32_e32 v93, v105, v91
	v_sub_f32_e32 v0, v95, v68
	v_pk_add_f32 v[66:67], v[92:93], v[106:107]
	v_exp_f32_e32 v93, v0
	v_sub_f32_e32 v0, v111, v68
	v_pk_add_f32 v[108:109], v[66:67], v[66:67] op_sel_hi:[0,1]
	v_exp_f32_e32 v107, v0
	v_sub_f32_e32 v0, v96, v68
	v_exp_f32_e32 v108, v0
	v_sub_f32_e32 v0, v112, v68
	v_exp_f32_e32 v94, v0
	v_add_f32_e32 v95, v107, v93
	v_exp_f32_e64 v0, -v68
	v_add_f32_e32 v212, v110, v97
	v_pk_add_f32 v[66:67], v[94:95], v[108:109]
	v_cvt_pk_bf16_f32 v169, v100, v87
	v_pk_add_f32 v[66:67], v[66:67], v[66:67] op_sel:[0,1] op_sel_hi:[1,0]
	v_pk_mul_f32 v[64:65], v[64:65], v[0:1] op_sel_hi:[1,0]
	v_mov_b32_e32 v67, v68
	v_pk_add_f32 v[212:213], v[212:213], v[66:67]
	v_pk_mul_f32 v[62:63], v[62:63], v[0:1] op_sel_hi:[1,0]
	v_xor_b32_e32 v66, 0x80000000, v213
	v_mov_b32_e32 v67, v66
	v_mov_b32_e32 v68, v66
	v_mov_b32_e32 v69, v66
	v_mov_b32_e32 v70, v66
	v_mov_b32_e32 v71, v66
	v_mov_b32_e32 v72, v66
	v_mov_b32_e32 v73, v66
	v_mov_b32_e32 v74, v66
	v_mov_b32_e32 v75, v66
	v_mov_b32_e32 v76, v66
	v_mov_b32_e32 v77, v66
	v_mov_b32_e32 v78, v66
	v_mov_b32_e32 v79, v66
	v_mov_b32_e32 v80, v66
	v_mov_b32_e32 v81, v66
	v_pk_mul_f32 v[60:61], v[60:61], v[0:1] op_sel_hi:[1,0]
	v_pk_mul_f32 v[58:59], v[58:59], v[0:1] op_sel_hi:[1,0]
	v_pk_mul_f32 v[56:57], v[56:57], v[0:1] op_sel_hi:[1,0]
	v_pk_mul_f32 v[54:55], v[54:55], v[0:1] op_sel_hi:[1,0]
	v_pk_mul_f32 v[52:53], v[52:53], v[0:1] op_sel_hi:[1,0]
	v_pk_mul_f32 v[50:51], v[50:51], v[0:1] op_sel_hi:[1,0]
	v_pk_mul_f32 v[48:49], v[48:49], v[0:1] op_sel_hi:[1,0]
	v_pk_mul_f32 v[46:47], v[46:47], v[0:1] op_sel_hi:[1,0]
	v_pk_mul_f32 v[44:45], v[44:45], v[0:1] op_sel_hi:[1,0]
	v_pk_mul_f32 v[42:43], v[42:43], v[0:1] op_sel_hi:[1,0]
	v_pk_mul_f32 v[40:41], v[40:41], v[0:1] op_sel_hi:[1,0]
	v_pk_mul_f32 v[38:39], v[38:39], v[0:1] op_sel_hi:[1,0]
	v_pk_mul_f32 v[36:37], v[36:37], v[0:1] op_sel_hi:[1,0]
	v_pk_mul_f32 v[34:35], v[34:35], v[0:1] op_sel_hi:[1,0]
	v_pk_mul_f32 v[32:33], v[32:33], v[0:1] op_sel_hi:[1,0]
	v_pk_mul_f32 v[30:31], v[30:31], v[0:1] op_sel_hi:[1,0]
	v_pk_mul_f32 v[28:29], v[28:29], v[0:1] op_sel_hi:[1,0]
	v_pk_mul_f32 v[26:27], v[26:27], v[0:1] op_sel_hi:[1,0]
	v_pk_mul_f32 v[24:25], v[24:25], v[0:1] op_sel_hi:[1,0]
	v_pk_mul_f32 v[22:23], v[22:23], v[0:1] op_sel_hi:[1,0]
	v_pk_mul_f32 v[20:21], v[20:21], v[0:1] op_sel_hi:[1,0]
	v_pk_mul_f32 v[18:19], v[18:19], v[0:1] op_sel_hi:[1,0]
	v_pk_mul_f32 v[16:17], v[16:17], v[0:1] op_sel_hi:[1,0]
	v_pk_mul_f32 v[14:15], v[14:15], v[0:1] op_sel_hi:[1,0]
	v_pk_mul_f32 v[12:13], v[12:13], v[0:1] op_sel_hi:[1,0]
	v_pk_mul_f32 v[10:11], v[10:11], v[0:1] op_sel_hi:[1,0]
	v_pk_mul_f32 v[8:9], v[8:9], v[0:1] op_sel_hi:[1,0]
	v_pk_mul_f32 v[6:7], v[6:7], v[0:1] op_sel_hi:[1,0]
	v_pk_mul_f32 v[4:5], v[4:5], v[0:1] op_sel_hi:[1,0]
	v_pk_mul_f32 v[2:3], v[2:3], v[0:1] op_sel_hi:[1,0]
	v_mul_f32_e32 v243, v243, v0
	v_cvt_pk_bf16_f32 v174, v102, v89
	v_cvt_pk_bf16_f32 v175, v104, v91
	v_cvt_pk_bf16_f32 v176, v106, v93
	v_cvt_pk_bf16_f32 v177, v108, v97
	v_cvt_pk_bf16_f32 v182, v117, v119
	v_cvt_pk_bf16_f32 v183, v82, v99
	v_cvt_pk_bf16_f32 v184, v84, v115
	v_cvt_pk_bf16_f32 v185, v86, v101
	v_cvt_pk_bf16_f32 v190, v88, v103
	v_cvt_pk_bf16_f32 v191, v90, v105
	v_cvt_pk_bf16_f32 v192, v92, v107
	v_cvt_pk_bf16_f32 v193, v94, v110

.LBB0_328:
	s_and_b64 vcc, exec, s[26:27]
	s_cbranch_vccz .LBB0_342
	s_lshl_b32 s26, s31, 14
	s_add_i32 s26, s26, 0
	s_nop 1
	ds_read_b128 v[126:129], v212 offset:49152
	s_waitcnt lgkmcnt(1)
	v_mfma_f32_32x32x16_bf16 v[82:97], v[98:101], v[146:149], v[66:81]
	ds_read_b128 v[122:125], v102 offset:8192
	v_mfma_f32_32x32x16_bf16 v[98:113], v[114:117], v[146:149], v[66:81]
	v_add_u32_e32 v139, s26, v241
	ds_read_b128 v[114:117], v139
	v_mfma_f32_32x32x16_bf16 v[82:97], v[118:121], v[150:153], v[82:97]
	ds_read_b128 v[118:121], v139 offset:8192
	s_waitcnt lgkmcnt(0)
	v_mfma_f32_32x32x16_bf16 v[98:113], v[122:125], v[150:153], v[98:113]
	v_add_u32_e32 v139, s26, v242
	ds_read_b128 v[122:125], v139
	v_mfma_f32_32x32x16_bf16 v[82:97], v[114:117], v[154:157], v[82:97]
	ds_read_b128 v[114:117], v139 offset:8192
	v_mfma_f32_32x32x16_bf16 v[98:113], v[118:121], v[154:157], v[98:113]
	s_waitcnt lgkmcnt(0)
	v_mfma_f32_32x32x16_bf16 v[82:97], v[122:125], v[158:161], v[82:97]
	v_mfma_f32_32x32x16_bf16 v[98:113], v[114:117], v[158:161], v[98:113]
	s_nop 0
	ds_read_b128 v[122:125], v212 offset:53248
	ds_read_b128 v[118:121], v212 offset:57344
	ds_read_b128 v[114:117], v212 offset:61440
	s_add_i32 s26, s20, 64
	s_cmp_le_u32 s26, s16
	s_cbranch_scc1 .LBB0_331
	v_add_u32_e32 v130, s20, v249
	v_add_u32_e32 v130, 0x6f, v130
	v_and_b32_e32 v130, 0x3ffffffc, v130
	v_lshl_add_u32 v162, v130, 2, v244
	ds_read_b128 v[130:133], v162
	ds_read_b128 v[134:137], v162 offset:16
	ds_read_b128 v[138:141], v162 offset:64
	ds_read_b128 v[142:145], v162 offset:80
	s_waitcnt lgkmcnt(0)
	v_pk_add_f32 v[84:85], v[84:85], v[132:133]
	v_pk_add_f32 v[86:87], v[86:87], v[134:135]
	v_pk_add_f32 v[90:91], v[90:91], v[138:139]
	v_pk_add_f32 v[94:95], v[94:95], v[142:143]
	v_pk_add_f32 v[96:97], v[96:97], v[144:145]
	v_pk_add_f32 v[92:93], v[92:93], v[140:141]
	v_pk_add_f32 v[88:89], v[88:89], v[136:137]
	v_pk_add_f32 v[82:83], v[82:83], v[130:131]
	ds_read_b128 v[130:133], v162 offset:128
	ds_read_b128 v[134:137], v162 offset:144
	ds_read_b128 v[138:141], v162 offset:192
	ds_read_b128 v[142:145], v162 offset:208
	s_waitcnt lgkmcnt(0)
	v_pk_add_f32 v[100:101], v[100:101], v[132:133]
	v_pk_add_f32 v[102:103], v[102:103], v[134:135]
	v_pk_add_f32 v[106:107], v[106:107], v[138:139]
	v_pk_add_f32 v[110:111], v[110:111], v[142:143]
	v_pk_add_f32 v[112:113], v[112:113], v[144:145]
	v_pk_add_f32 v[108:109], v[108:109], v[140:141]
	v_pk_add_f32 v[104:105], v[104:105], v[136:137]
	v_pk_add_f32 v[98:99], v[98:99], v[130:131]
.LBB0_331:
	s_waitcnt lgkmcnt(3)
	v_mfma_f32_32x32x16_bf16 v[50:65], v[126:129], v[166:169], v[50:65]
	ds_read_b128 v[126:129], v0 offset:49152
	s_nop 0
	v_exp_f32_e32 v130, v82
	v_exp_f32_e32 v131, v83
	v_add_f32_e32 v132, v1, v130
	v_add_f32_e32 v133, v1, v131
	v_cvt_pk_bf16_f32 v162, v130, v131
	s_waitcnt lgkmcnt(3)
	v_mfma_f32_32x32x16_bf16 v[34:49], v[122:125], v[166:169], v[34:49]
	ds_read_b128 v[122:125], v0 offset:53248
	v_exp_f32_e32 v130, v84
	v_exp_f32_e32 v131, v85
	s_add_i32 s22, s22, 3
	s_cmp_le_u32 s22, s17
	v_add_f32_e32 v132, v132, v130
	v_add_f32_e32 v133, v133, v131
	v_cvt_pk_bf16_f32 v163, v130, v131
	s_cselect_b64 s[26:27], -1, 0
	s_cmp_gt_u32 s22, s17
	v_lshl_add_u64 v[130:131], s[8:9], 0, v[214:215]
	s_cbranch_scc1 .LBB0_333
	s_lshl_b32 s22, s28, 14
	v_lshl_add_u64 v[134:135], v[130:131], 0, s[50:51]
	s_add_i32 m0, s10, s22
	s_nop 0
	global_load_lds_dwordx4 v[134:135], off
.LBB0_333:
	s_waitcnt lgkmcnt(3)
	v_mfma_f32_32x32x16_bf16 v[18:33], v[118:121], v[166:169], v[18:33]
	ds_read_b128 v[118:121], v0 offset:57344
	v_exp_f32_e32 v134, v86
	v_exp_f32_e32 v135, v87
	v_add_f32_e32 v132, v132, v134
	v_add_f32_e32 v133, v133, v135
	v_cvt_pk_bf16_f32 v164, v134, v135
	s_waitcnt lgkmcnt(3)
	v_mfma_f32_32x32x16_bf16 v[2:17], v[114:117], v[166:169], v[2:17]
	ds_read_b128 v[114:117], v0 offset:61440
	v_exp_f32_e32 v0, v88
	v_exp_f32_e32 v134, v89
	v_add_f32_e32 v132, v132, v0
	v_add_f32_e32 v133, v133, v134
	v_cvt_pk_bf16_f32 v165, v0, v134
	s_waitcnt lgkmcnt(3)
	v_mfma_f32_32x32x16_bf16 v[50:65], v[126:129], v[174:177], v[50:65]
	v_add_u32_e32 v0, s36, v247
	ds_read_b128 v[126:129], v0 offset:49152
	v_exp_f32_e32 v134, v90
	v_exp_f32_e32 v135, v91
	v_add_f32_e32 v132, v132, v134
	v_add_f32_e32 v133, v133, v135
	v_cvt_pk_bf16_f32 v170, v134, v135
	s_waitcnt lgkmcnt(3)
	v_mfma_f32_32x32x16_bf16 v[34:49], v[122:125], v[174:177], v[34:49]
	ds_read_b128 v[122:125], v0 offset:53248
	v_exp_f32_e32 v134, v92
	v_exp_f32_e32 v135, v93
	v_add_f32_e32 v132, v132, v134
	v_add_f32_e32 v133, v133, v135
	s_andn2_b64 vcc, exec, s[26:27]
	v_cvt_pk_bf16_f32 v171, v134, v135
	s_cbranch_vccnz .LBB0_335
	s_lshl_b32 s22, s28, 14
	s_add_i32 s22, s10, s22
	v_lshl_add_u64 v[130:131], v[130:131], 0, s[4:5]
	s_add_i32 m0, s22, 0x2000
	s_nop 0
	global_load_lds_dwordx4 v[130:131], off
.LBB0_335:
	s_waitcnt lgkmcnt(3)
	v_mfma_f32_32x32x16_bf16 v[18:33], v[118:121], v[174:177], v[18:33]
	ds_read_b128 v[118:121], v0 offset:57344
	v_exp_f32_e32 v130, v94
	v_exp_f32_e32 v131, v95
	v_add_f32_e32 v132, v132, v130
	v_add_f32_e32 v133, v133, v131
	v_cvt_pk_bf16_f32 v172, v130, v131
	s_waitcnt lgkmcnt(3)
	v_mfma_f32_32x32x16_bf16 v[2:17], v[114:117], v[174:177], v[2:17]
	ds_read_b128 v[114:117], v0 offset:61440
	v_exp_f32_e32 v0, v96
	v_exp_f32_e32 v130, v97
	v_add_f32_e32 v131, v132, v0
	v_add_f32_e32 v132, v133, v130
	v_cvt_pk_bf16_f32 v173, v0, v130
	s_waitcnt lgkmcnt(3)
	v_mfma_f32_32x32x16_bf16 v[50:65], v[126:129], v[182:185], v[50:65]
	v_add_u32_e32 v0, s36, v248
	ds_read_b128 v[126:129], v0 offset:49152
	v_exp_f32_e32 v130, v98
	v_exp_f32_e32 v133, v99
	v_add_f32_e32 v131, v131, v130
	v_add_f32_e32 v134, v132, v133
	v_cvt_pk_bf16_f32 v178, v130, v133
	s_waitcnt lgkmcnt(3)
	v_mfma_f32_32x32x16_bf16 v[34:49], v[122:125], v[182:185], v[34:49]
	v_exp_f32_e32 v130, v100
	v_exp_f32_e32 v135, v101
	ds_read_b128 v[122:125], v0 offset:53248
	v_add_f32_e32 v132, v131, v130
	v_add_f32_e32 v133, v134, v135
	v_cvt_pk_bf16_f32 v179, v130, v135
	v_cndmask_b32_e64 v130, 0, 1, s[44:45]
	v_cmp_ne_u32_e64 s[40:41], 1, v130
	s_andn2_b64 vcc, exec, s[44:45]
	v_lshl_add_u64 v[130:131], s[8:9], 0, v[216:217]
	s_cbranch_vccnz .LBB0_337
	s_lshl_b32 s22, s23, 14
	s_add_i32 s22, s10, s22
	s_add_i32 m0, s22, 0xc000
	s_add_u32 s100, s8, s0
	s_addc_u32 s101, s9, s1
	global_load_lds_dwordx4 v216, s[100:101]
.LBB0_337:
	s_waitcnt lgkmcnt(3)
	v_mfma_f32_32x32x16_bf16 v[18:33], v[118:121], v[182:185], v[18:33]
	ds_read_b128 v[118:121], v0 offset:57344
	v_exp_f32_e32 v134, v102
	v_exp_f32_e32 v135, v103
	v_add_f32_e32 v132, v132, v134
	v_add_f32_e32 v133, v133, v135
	v_cvt_pk_bf16_f32 v180, v134, v135
	s_waitcnt lgkmcnt(3)
	v_mfma_f32_32x32x16_bf16 v[2:17], v[114:117], v[182:185], v[2:17]
	ds_read_b128 v[114:117], v0 offset:61440
	v_exp_f32_e32 v0, v104
	v_exp_f32_e32 v134, v105
	v_add_f32_e32 v132, v132, v0
	v_add_f32_e32 v133, v133, v134
	v_cvt_pk_bf16_f32 v181, v0, v134
	s_waitcnt lgkmcnt(3)
	v_mfma_f32_32x32x16_bf16 v[50:65], v[126:129], v[190:193], v[50:65]
	v_exp_f32_e32 v0, v106
	v_exp_f32_e32 v126, v107
	v_add_f32_e32 v127, v132, v0
	v_add_f32_e32 v128, v133, v126
	v_cvt_pk_bf16_f32 v186, v0, v126
	s_waitcnt lgkmcnt(2)
	v_mfma_f32_32x32x16_bf16 v[34:49], v[122:125], v[190:193], v[34:49]
	v_exp_f32_e32 v123, v108
	v_exp_f32_e32 v124, v109
	v_add_f32_e32 v0, v127, v123
	v_add_f32_e32 v122, v128, v124
	s_and_b64 vcc, exec, s[40:41]
	v_cvt_pk_bf16_f32 v187, v123, v124
	s_cbranch_vccnz .LBB0_339
	s_lshl_b32 s22, s23, 14
	s_add_i32 s22, s10, s22
	v_lshl_add_u64 v[124:125], v[130:131], 0, s[52:53]
	s_add_i32 m0, s22, 0xe000
	s_nop 0
	global_load_lds_dwordx4 v[124:125], off
.LBB0_339:
	s_waitcnt lgkmcnt(1)
	v_mfma_f32_32x32x16_bf16 v[18:33], v[118:121], v[190:193], v[18:33]
	v_exp_f32_e32 v118, v110
	v_exp_f32_e32 v119, v111
	v_add_f32_e32 v0, v0, v118
	v_add_f32_e32 v120, v122, v119
	v_cvt_pk_bf16_f32 v188, v118, v119
	s_waitcnt lgkmcnt(0)
	v_mfma_f32_32x32x16_bf16 v[2:17], v[114:117], v[190:193], v[2:17]
	v_exp_f32_e32 v114, v112
	v_exp_f32_e32 v115, v113
	v_add_f32_e32 v0, v0, v114
	v_add_f32_e32 v116, v120, v115
	v_cvt_pk_bf16_f32 v189, v114, v115
	v_add_f32_e32 v212, v0, v116
	v_cmp_nge_f32_e32 vcc, s7, v212
	s_cbranch_vccz .LBB0_341
	v_max_f32_e32 v0, v99, v99
	v_max_f32_e32 v66, v83, v83
	v_max_f32_e32 v0, v66, v0
	v_max3_f32 v0, v82, v98, v0
	v_max3_f32 v66, v100, v85, v101
	v_max3_f32 v0, v0, v84, v66
	v_max3_f32 v66, v102, v87, v103
	v_max3_f32 v0, v0, v86, v66
	v_max3_f32 v66, v104, v89, v105
	v_max3_f32 v0, v0, v88, v66
	v_max3_f32 v66, v106, v91, v107
	v_max3_f32 v0, v0, v90, v66
	v_max3_f32 v66, v108, v93, v109
	v_max3_f32 v0, v0, v92, v66
	v_max3_f32 v66, v110, v95, v111
	v_max3_f32 v0, v0, v94, v66
	v_max3_f32 v66, v112, v97, v113
	v_max3_f32 v0, v0, v96, v66
	v_mov_b32_e32 v66, v0
	s_nop 1
	v_permlane32_swap_b32_e32 v0, v66
	v_max_f32_e32 v66, v66, v66
	v_max_f32_e32 v0, v0, v0
	v_max_f32_e32 v0, v0, v66
	v_cmp_lt_f32_e32 vcc, s57, v0
	s_nop 1
	v_cndmask_b32_e32 v68, 0, v0, vcc
	v_sub_f32_e32 v0, v82, v68
	v_exp_f32_e32 v116, v0
	v_sub_f32_e32 v0, v98, v68
	v_exp_f32_e32 v117, v0
	v_sub_f32_e32 v0, v83, v68
	v_exp_f32_e32 v118, v0
	v_sub_f32_e32 v0, v99, v68
	v_exp_f32_e32 v119, v0
	v_sub_f32_e32 v0, v84, v68
	v_exp_f32_e32 v114, v0
	v_sub_f32_e32 v0, v100, v68
	v_exp_f32_e32 v82, v0
	v_add_f32_e32 v0, v116, v117
	v_add_f32_e32 v83, 0, v0
	v_add_f32_e32 v115, v118, v119
	v_sub_f32_e32 v0, v85, v68
	v_pk_add_f32 v[66:67], v[114:115], v[82:83]
	v_exp_f32_e32 v83, v0
	v_sub_f32_e32 v0, v101, v68
	v_exp_f32_e32 v115, v0
	v_sub_f32_e32 v0, v86, v68
	v_pk_add_f32 v[98:99], v[66:67], v[66:67] op_sel_hi:[0,1]
	v_exp_f32_e32 v100, v0
	v_sub_f32_e32 v0, v102, v68
	v_exp_f32_e32 v98, v0
	v_add_f32_e32 v101, v83, v115
	v_sub_f32_e32 v0, v87, v68
	v_cvt_pk_bf16_f32 v162, v116, v118
	v_pk_add_f32 v[66:67], v[100:101], v[98:99]
	v_exp_f32_e32 v99, v0
	v_sub_f32_e32 v0, v103, v68
	v_exp_f32_e32 v101, v0
	v_sub_f32_e32 v0, v88, v68
	v_pk_add_f32 v[84:85], v[66:67], v[66:67] op_sel_hi:[0,1]
	v_exp_f32_e32 v102, v0
	v_sub_f32_e32 v0, v104, v68
	v_exp_f32_e32 v84, v0
	v_add_f32_e32 v103, v99, v101
	v_sub_f32_e32 v0, v89, v68
	v_cvt_pk_bf16_f32 v163, v114, v83
	v_pk_add_f32 v[66:67], v[102:103], v[84:85]
	v_exp_f32_e32 v85, v0
	v_sub_f32_e32 v0, v105, v68
	v_exp_f32_e32 v103, v0
	v_sub_f32_e32 v0, v90, v68
	v_pk_add_f32 v[86:87], v[66:67], v[66:67] op_sel_hi:[0,1]
	v_exp_f32_e32 v104, v0
	v_sub_f32_e32 v0, v106, v68
	v_exp_f32_e32 v86, v0
	v_add_f32_e32 v105, v85, v103
	v_sub_f32_e32 v0, v91, v68
	v_cvt_pk_bf16_f32 v164, v100, v99
	v_pk_add_f32 v[66:67], v[104:105], v[86:87]
	v_exp_f32_e32 v87, v0
	v_sub_f32_e32 v0, v107, v68
	v_exp_f32_e32 v105, v0
	v_sub_f32_e32 v0, v92, v68
	v_pk_add_f32 v[88:89], v[66:67], v[66:67] op_sel_hi:[0,1]
	v_exp_f32_e32 v90, v0
	v_sub_f32_e32 v0, v108, v68
	v_exp_f32_e32 v88, v0
	v_sub_f32_e32 v0, v97, v68
	v_exp_f32_e32 v97, v0
	v_add_f32_e32 v91, v87, v105
	v_sub_f32_e32 v0, v93, v68
	v_pk_add_f32 v[66:67], v[90:91], v[88:89]
	v_exp_f32_e32 v89, v0
	v_sub_f32_e32 v0, v109, v68
	v_exp_f32_e32 v91, v0
	v_sub_f32_e32 v0, v94, v68
	v_pk_add_f32 v[106:107], v[66:67], v[66:67] op_sel_hi:[0,1]
	v_exp_f32_e32 v92, v0
	v_sub_f32_e32 v0, v110, v68
	v_exp_f32_e32 v106, v0
	v_sub_f32_e32 v0, v113, v68
	v_exp_f32_e32 v110, v0
	v_add_f32_e32 v93, v89, v91
	v_sub_f32_e32 v0, v95, v68
	v_pk_add_f32 v[66:67], v[92:93], v[106:107]
	v_exp_f32_e32 v93, v0
	v_sub_f32_e32 v0, v111, v68
	v_exp_f32_e32 v107, v0
	v_sub_f32_e32 v0, v96, v68
	v_pk_add_f32 v[108:109], v[66:67], v[66:67] op_sel_hi:[0,1]
	v_exp_f32_e32 v94, v0
	v_sub_f32_e32 v0, v112, v68
	v_exp_f32_e32 v108, v0
	v_add_f32_e32 v95, v93, v107
	v_exp_f32_e64 v0, -v68
	v_add_f32_e32 v212, v97, v110
	v_pk_add_f32 v[66:67], v[94:95], v[108:109]
	v_cvt_pk_bf16_f32 v165, v102, v85
	v_pk_add_f32 v[66:67], v[66:67], v[66:67] op_sel:[0,1] op_sel_hi:[1,0]
	v_pk_mul_f32 v[64:65], v[64:65], v[0:1] op_sel_hi:[1,0]
	v_mov_b32_e32 v67, v68
	v_pk_add_f32 v[212:213], v[212:213], v[66:67]
	v_pk_mul_f32 v[62:63], v[62:63], v[0:1] op_sel_hi:[1,0]
	v_xor_b32_e32 v66, 0x80000000, v213
	v_mov_b32_e32 v67, v66
	v_mov_b32_e32 v68, v66
	v_mov_b32_e32 v69, v66
	v_mov_b32_e32 v70, v66
	v_mov_b32_e32 v71, v66
	v_mov_b32_e32 v72, v66
	v_mov_b32_e32 v73, v66
	v_mov_b32_e32 v74, v66
	v_mov_b32_e32 v75, v66
	v_mov_b32_e32 v76, v66
	v_mov_b32_e32 v77, v66
	v_mov_b32_e32 v78, v66
	v_mov_b32_e32 v79, v66
	v_mov_b32_e32 v80, v66
	v_mov_b32_e32 v81, v66
	v_pk_mul_f32 v[60:61], v[60:61], v[0:1] op_sel_hi:[1,0]
	v_pk_mul_f32 v[58:59], v[58:59], v[0:1] op_sel_hi:[1,0]
	v_pk_mul_f32 v[56:57], v[56:57], v[0:1] op_sel_hi:[1,0]
	v_pk_mul_f32 v[54:55], v[54:55], v[0:1] op_sel_hi:[1,0]
	v_pk_mul_f32 v[52:53], v[52:53], v[0:1] op_sel_hi:[1,0]
	v_pk_mul_f32 v[50:51], v[50:51], v[0:1] op_sel_hi:[1,0]
	v_pk_mul_f32 v[48:49], v[48:49], v[0:1] op_sel_hi:[1,0]
	v_pk_mul_f32 v[46:47], v[46:47], v[0:1] op_sel_hi:[1,0]
	v_pk_mul_f32 v[44:45], v[44:45], v[0:1] op_sel_hi:[1,0]
	v_pk_mul_f32 v[42:43], v[42:43], v[0:1] op_sel_hi:[1,0]
	v_pk_mul_f32 v[40:41], v[40:41], v[0:1] op_sel_hi:[1,0]
	v_pk_mul_f32 v[38:39], v[38:39], v[0:1] op_sel_hi:[1,0]
	v_pk_mul_f32 v[36:37], v[36:37], v[0:1] op_sel_hi:[1,0]
	v_pk_mul_f32 v[34:35], v[34:35], v[0:1] op_sel_hi:[1,0]
	v_pk_mul_f32 v[32:33], v[32:33], v[0:1] op_sel_hi:[1,0]
	v_pk_mul_f32 v[30:31], v[30:31], v[0:1] op_sel_hi:[1,0]
	v_pk_mul_f32 v[28:29], v[28:29], v[0:1] op_sel_hi:[1,0]
	v_pk_mul_f32 v[26:27], v[26:27], v[0:1] op_sel_hi:[1,0]
	v_pk_mul_f32 v[24:25], v[24:25], v[0:1] op_sel_hi:[1,0]
	v_pk_mul_f32 v[22:23], v[22:23], v[0:1] op_sel_hi:[1,0]
	v_pk_mul_f32 v[20:21], v[20:21], v[0:1] op_sel_hi:[1,0]
	v_pk_mul_f32 v[18:19], v[18:19], v[0:1] op_sel_hi:[1,0]
	v_pk_mul_f32 v[16:17], v[16:17], v[0:1] op_sel_hi:[1,0]
	v_pk_mul_f32 v[14:15], v[14:15], v[0:1] op_sel_hi:[1,0]
	v_pk_mul_f32 v[12:13], v[12:13], v[0:1] op_sel_hi:[1,0]
	v_pk_mul_f32 v[10:11], v[10:11], v[0:1] op_sel_hi:[1,0]
	v_pk_mul_f32 v[8:9], v[8:9], v[0:1] op_sel_hi:[1,0]
	v_pk_mul_f32 v[6:7], v[6:7], v[0:1] op_sel_hi:[1,0]
	v_pk_mul_f32 v[4:5], v[4:5], v[0:1] op_sel_hi:[1,0]
	v_pk_mul_f32 v[2:3], v[2:3], v[0:1] op_sel_hi:[1,0]
	v_mul_f32_e32 v243, v243, v0
	v_cvt_pk_bf16_f32 v170, v104, v87
	v_cvt_pk_bf16_f32 v171, v90, v89
	v_cvt_pk_bf16_f32 v172, v92, v93
	v_cvt_pk_bf16_f32 v173, v94, v97
	v_cvt_pk_bf16_f32 v178, v117, v119
	v_cvt_pk_bf16_f32 v179, v82, v115
	v_cvt_pk_bf16_f32 v180, v98, v101
	v_cvt_pk_bf16_f32 v181, v84, v103
	v_cvt_pk_bf16_f32 v186, v86, v105
	v_cvt_pk_bf16_f32 v187, v88, v91
	v_cvt_pk_bf16_f32 v188, v106, v107
	v_cvt_pk_bf16_f32 v189, v108, v110
